# BI: grid barrier issues the L1 invalidate (buffer_inv sc1) right after the arrival atomic instead of after the release is observed; no L1-allocating load is issued in between
# speedup vs baseline: 1.1185x; 1.0196x over previous
; __device__ __forceinline__ unsigned xb_ld(unsigned* p)              { return __hip_atomic_load(p, __ATOMIC_RELAXED, __HIP_MEMORY_SCOPE_AGENT); }
; __device__ __forceinline__ unsigned xb_add(unsigned* p, unsigned v) { return __hip_atomic_fetch_add(p, v, __ATOMIC_RELAXED, __HIP_MEMORY_SCOPE_AGENT); }
; #define XB_SPIN(cond, bar) do { unsigned _sp = 0; while (cond) { __builtin_amdgcn_s_sleep(1); \
;     if ((++_sp & 255u) == 0u) { if (xb_ld(&(bar)[XB_TMO])) break; if (_sp > XB_SPIN_CAP) { atomicAdd(&(bar)[XB_TMO], 1u); break; } } } } while (0)
; __device__ __forceinline__ void xcd_barrier(const XcdBarrier& b) {
;     ...
;     if (threadIdx.x == 0) {
;         unsigned* bar = b.bar;
;         __builtin_amdgcn_s_waitcnt(0);
;         unsigned nloc = b.st[0], nx = b.st[1];
;         if (nloc == 0u) { xcd_barrier_complete(bar, b.x, nloc, nx); b.st[0] = nloc; b.st[1] = nx; }
;         const unsigned old = xb_add(&bar[XB_XSUB(b.x)], 1u);
;         const unsigned gen = old / nloc;
;         if (old + 1u == (gen + 1u) * nloc) {
;             __builtin_amdgcn_fence(__ATOMIC_RELEASE, "agent");
;             asm volatile("s_waitcnt vmcnt(0)" ::: "memory");
;             const unsigned og = xb_add(&bar[XB_TOP], 1u);
;             const unsigned tg = og / nx;
;             if (og + 1u == (tg + 1u) * nx) xb_add(&bar[XB_TOPGEN], 1u);
;             else XB_SPIN(xb_ld(&bar[XB_TOPGEN]) == tg, bar);
;             __builtin_amdgcn_fence(__ATOMIC_ACQUIRE, "agent");
;             xb_add(&bar[XB_XGEN(b.x)], 1u);
;             asm volatile("s_waitcnt vmcnt(0)" ::: "memory");
;         } else {
;             XB_SPIN(xb_ld(&bar[XB_XGEN(b.x)]) == gen, bar);
;             __builtin_amdgcn_fence(__ATOMIC_ACQUIRE, "agent");
;             asm volatile("s_waitcnt vmcnt(0)" ::: "memory");
;         }
.LBB0_754:
	s_or_b64 exec, exec, s[4:5]
	v_cvt_f32_u32_e32 v4, v2
	s_waitcnt vmcnt(0)
	buffer_inv sc1
	v_readfirstlane_b32 s2, v3
	v_sub_u32_e32 v3, 0, v2
	v_rcp_iflag_f32_e32 v4, v4
	v_add_u32_e32 v5, s2, v1
	v_mul_f32_e32 v4, 0x4f7ffffe, v4
	v_cvt_u32_f32_e32 v4, v4
	v_mul_lo_u32 v1, v3, v4
	v_mul_hi_u32 v1, v4, v1
	v_add_u32_e32 v1, v4, v1
	v_mul_hi_u32 v1, v5, v1
	v_mul_lo_u32 v3, v1, v2
	v_sub_u32_e32 v3, v5, v3
	v_add_u32_e32 v4, 1, v1
	v_cmp_ge_u32_e32 vcc, v3, v2
	s_nop 1
	v_cndmask_b32_e32 v1, v1, v4, vcc
	v_sub_u32_e32 v4, v3, v2
	v_cndmask_b32_e32 v3, v3, v4, vcc
	v_add_u32_e32 v4, 1, v1
	v_cmp_ge_u32_e32 vcc, v3, v2
	v_add_u32_e32 v3, 1, v5
	s_nop 0
	v_cndmask_b32_e32 v1, v1, v4, vcc
	v_mul_lo_u32 v4, v2, v1
	v_add_u32_e32 v2, v4, v2
	v_cmp_ne_u32_e32 vcc, v3, v2
	s_and_saveexec_b64 s[4:5], vcc
	s_xor_b64 s[4:5], exec, s[4:5]
	s_cbranch_execz .LBB0_768
	v_readlane_b32 s6, v254, 15
	v_readlane_b32 s7, v254, 16
	s_waitcnt lgkmcnt(0)
	s_nop 3
	global_load_dword v0, v97, s[6:7] sc1
	s_waitcnt vmcnt(0)
	v_cmp_eq_u32_e32 vcc, v0, v1
	s_and_saveexec_b64 s[6:7], vcc
	s_cbranch_execz .LBB0_767
	s_mov_b32 s2, 1
	s_mov_b64 s[20:21], 0
	s_branch .LBB0_758

; __device__ __forceinline__ unsigned xb_ld(unsigned* p)              { return __hip_atomic_load(p, __ATOMIC_RELAXED, __HIP_MEMORY_SCOPE_AGENT); }
; __device__ __forceinline__ unsigned xb_add(unsigned* p, unsigned v) { return __hip_atomic_fetch_add(p, v, __ATOMIC_RELAXED, __HIP_MEMORY_SCOPE_AGENT); }
; #define XB_SPIN(cond, bar) do { unsigned _sp = 0; while (cond) { __builtin_amdgcn_s_sleep(1); \
;     if ((++_sp & 255u) == 0u) { if (xb_ld(&(bar)[XB_TMO])) break; if (_sp > XB_SPIN_CAP) { atomicAdd(&(bar)[XB_TMO], 1u); break; } } } } while (0)
; __device__ __forceinline__ void xcd_barrier(const XcdBarrier& b) {
;     ...
;         const unsigned old = xb_add(&bar[XB_XSUB(b.x)], 1u);
;         const unsigned gen = old / nloc;
;         if (old + 1u == (gen + 1u) * nloc) {
;             __builtin_amdgcn_fence(__ATOMIC_RELEASE, "agent");
;             asm volatile("s_waitcnt vmcnt(0)" ::: "memory");
;             const unsigned og = xb_add(&bar[XB_TOP], 1u);
;             const unsigned tg = og / nx;
;             if (og + 1u == (tg + 1u) * nx) xb_add(&bar[XB_TOPGEN], 1u);
;             else XB_SPIN(xb_ld(&bar[XB_TOPGEN]) == tg, bar);
;             __builtin_amdgcn_fence(__ATOMIC_ACQUIRE, "agent");
;             xb_add(&bar[XB_XGEN(b.x)], 1u);
.LBB0_767:
	s_or_b64 exec, exec, s[6:7]
	s_waitcnt vmcnt(0)
.LBB0_768:
	s_andn2_saveexec_b64 s[4:5], s[4:5]
	s_cbranch_execz .LBB0_788
	s_mov_b64 s[4:5], exec
	buffer_wbl2 sc1
	s_waitcnt lgkmcnt(0)
	s_waitcnt vmcnt(0)
	v_mbcnt_lo_u32_b32 v1, s4, 0
	v_mbcnt_hi_u32_b32 v1, s5, v1
	v_cmp_eq_u32_e32 vcc, 0, v1
	s_and_saveexec_b64 s[6:7], vcc
	s_cbranch_execz .LBB0_771
	s_bcnt1_i32_b64 s2, s[4:5]
	v_readlane_b32 s4, v254, 17
	v_mov_b32_e32 v2, s2
	v_readlane_b32 s5, v254, 18
	s_nop 4
	global_atomic_add v2, v97, v2, s[4:5] sc0

; __device__ __forceinline__ unsigned xb_ld(unsigned* p)              { return __hip_atomic_load(p, __ATOMIC_RELAXED, __HIP_MEMORY_SCOPE_AGENT); }
; __device__ __forceinline__ unsigned xb_add(unsigned* p, unsigned v) { return __hip_atomic_fetch_add(p, v, __ATOMIC_RELAXED, __HIP_MEMORY_SCOPE_AGENT); }
; #define XB_SPIN(cond, bar) do { unsigned _sp = 0; while (cond) { __builtin_amdgcn_s_sleep(1); \
;     if ((++_sp & 255u) == 0u) { if (xb_ld(&(bar)[XB_TMO])) break; if (_sp > XB_SPIN_CAP) { atomicAdd(&(bar)[XB_TMO], 1u); break; } } } } while (0)
; __device__ __forceinline__ void xcd_barrier(const XcdBarrier& b) {
;     ...
;             const unsigned og = xb_add(&bar[XB_TOP], 1u);
;             const unsigned tg = og / nx;
;             if (og + 1u == (tg + 1u) * nx) xb_add(&bar[XB_TOPGEN], 1u);
;             else XB_SPIN(xb_ld(&bar[XB_TOPGEN]) == tg, bar);
;             __builtin_amdgcn_fence(__ATOMIC_ACQUIRE, "agent");
;             xb_add(&bar[XB_XGEN(b.x)], 1u);
.LBB0_785:
	s_or_b64 exec, exec, s[4:5]
	s_mov_b64 s[4:5], exec
	v_mbcnt_lo_u32_b32 v0, s4, 0
	v_mbcnt_hi_u32_b32 v0, s5, v0
	v_cmp_eq_u32_e32 vcc, 0, v0
	s_waitcnt vmcnt(0)
	s_and_saveexec_b64 s[6:7], vcc
	s_cbranch_execz .LBB0_787
	s_bcnt1_i32_b64 s2, s[4:5]
	v_readlane_b32 s4, v254, 15
	v_mov_b32_e32 v0, s2
	v_readlane_b32 s5, v254, 16
	s_nop 4
	global_atomic_add v97, v0, s[4:5]
